# post-P0 grid sync replaced by a single counter barrier; rwkv_post: g and bonus loads issued with the y/v loads, loop-invariant parameter vectors hoisted
# baseline (speedup 1.0000x reference)
; __global__ void __launch_bounds__(512, 2) mega_fwd(Params p) {
;     ...
;     grid.sync();
.LBB0_210:
	v_lshrrev_b32_e32 v1, 20, v0
	v_lshrrev_b32_e32 v0, 10, v0
	v_or_b32_e32 v0, v0, v1
	s_movk_i32 s3, 0x3ff
	v_and_or_b32 v0, v0, s3, v210
	v_cmp_eq_u32_e32 vcc, 0, v0
	s_barrier
	s_and_saveexec_b64 s[4:5], vcc
	s_cbranch_execz .LBB0_220
	buffer_wbl2 sc1
	s_waitcnt vmcnt(0)
	s_load_dwordx2 s[6:7], s[0:1], 0xc8
	v_mov_b32_e32 v2, 0
	v_mov_b32_e32 v3, 1
	s_waitcnt lgkmcnt(0)
	s_add_u32 s6, s6, 0xea60
	s_addc_u32 s7, s7, 0
	global_atomic_add v2, v3, s[6:7]
.Lgs_spin:
	s_sleep 1
	global_load_dword v1, v2, s[6:7] sc1
	s_waitcnt vmcnt(0)
	v_cmp_gt_u32_e32 vcc, s58, v1
	s_cbranch_vccnz .Lgs_spin
	buffer_inv sc1

; __device__ __forceinline__ const float* arg_in(int k) { const char AS4* ka = (const char AS4*)__builtin_amdgcn_kernarg_segment_ptr(); asm volatile("" : "+s"(ka)); return *(const float* const AS4*)(ka + 8 * k); }
; __device__ __forceinline__ float sum8(float x) { x += dppf<0xB1>(x); x += dppf<0x4E>(x); x += dppf<0x141>(x); return x; }
; __device__ __forceinline__ void rwkv_post(int l, const bf16_t* PROJ, const bf16_t* LO, bf16_t* YR, const float* BON, int gtid, int nthr) {
;     const float* mu = arg_in(7) + (size_t)l * 3360 + 2048; const float* lnw = arg_in(16) + (size_t)l * 1024; const float* lnb = arg_in(17) + (size_t)l * 1024;
;     for (int it = gtid; it < TT * 128; it += nthr) {
;         const int T = it >> 7, cgp = it & 127, c0 = 8 * cgp, h = cgp >> 3;
;         float yv[8], zc[8], zp[8], gg[8];
;         unpack8(*(const u32x4*)(YR + (size_t)T * 1024 + c0), yv);
;         const bf16_t* vp = PROJ + (size_t)T * NP + C_RW + 2048 + c0;
;         unpack8(*(const u32x4*)vp, zc);
;         if ((T & (SEQ - 1)) != 0) unpack8(*(const u32x4*)(vp - NP), zp); else {
; #pragma unroll
;             for (int e = 0; e < 8; ++e) zp[e] = 0.f; }
;         unpack8(*(const u32x4*)(LO + (size_t)T * NLORA + 2048 + c0), gg);
;         float sm = 0.f;
; #pragma unroll
;         for (int e = 0; e < 8; ++e) sm += yv[e];
;         const float mean = sum8(sm) * (1.0f / 64.0f);
;         float sq = 0.f;
; #pragma unroll
;         for (int e = 0; e < 8; ++e) { const float d = yv[e] - mean; sq += d * d; }
;         const float rstd = rsqrtf(sum8(sq) * (1.0f / 64.0f) + GN_EPS);
;         const float bon = BON[(size_t)T * 16 + h];
;         const f32x4 m0 = *(const f32x4*)(mu + c0), m1 = *(const f32x4*)(mu + c0 + 4), w0 = *(const f32x4*)(lnw + c0), w1 = *(const f32x4*)(lnw + c0 + 4), b0 = *(const f32x4*)(lnb + c0), b1 = *(const f32x4*)(lnb + c0 + 4);
;         float out[8];
; #pragma unroll
;         for (int e = 0; e < 8; ++e) { const float mm = e < 4 ? m0[e] : m1[e - 4], ww = e < 4 ? w0[e] : w1[e - 4], bb = e < 4 ? b0[e] : b1[e - 4];
;             const float v = zc[e] + (zp[e] - zc[e]) * mm; out[e] = ((yv[e] - mean) * rstd * ww + bb + bon * v) * gg[e]; }
.LBB0_805:
	s_or_b64 exec, exec, s[30:31]
	v_mov_b32_e32 v1, v210
	v_readlane_b32 s2, v253, 3
	s_waitcnt lgkmcnt(0)
	s_barrier
	s_mov_b64 s[34:35], s[0:1]
	v_add_u32_e32 v27, s2, v1
	s_mov_b32 s2, 0x200000
	s_mov_b64 s[36:37], s[0:1]
	s_mov_b64 s[42:43], s[0:1]
	s_mov_b64 s[38:39], s[0:1]
	s_mov_b64 s[40:41], s[0:1]
	s_mov_b64 s[46:47], s[0:1]
	s_mov_b64 s[48:49], s[0:1]
	v_cmp_gt_i32_e32 vcc, s2, v27
	s_and_saveexec_b64 s[30:31], vcc
	s_cbranch_execz .LBB0_810
	v_readlane_b32 s12, v255, 16
	s_load_dwordx2 s[34:35], s[34:35], 0xc8
	s_nop 0
	s_load_dwordx2 s[36:37], s[36:37], 0xc8
	s_nop 0
	s_load_dwordx2 s[4:5], s[42:43], 0xc8
	s_load_dwordx2 s[24:25], s[48:49], 0x88
	s_load_dwordx2 s[26:27], s[38:39], 0xc8
	s_load_dwordx2 s[28:29], s[46:47], 0x80
	s_nop 0
	s_load_dwordx2 s[38:39], s[40:41], 0x38
	v_readlane_b32 s13, v255, 17
	s_lshl_b64 s[40:41], s[12:13], 2
	s_waitcnt lgkmcnt(0)
	s_add_u32 s24, s24, s40
	v_and_b32_e32 v4, 0x7f, v1
	s_addc_u32 s25, s25, s41
	v_lshlrev_b32_e32 v2, 4, v4
	v_mov_b32_e32 v3, v0
	s_add_u32 s28, s28, s40
	v_lshl_add_u64 v[2:3], s[4:5], 0, v[2:3]
	s_mov_b64 s[4:5], 0x2c300000
	v_lshrrev_b32_e32 v1, 1, v1
	s_addc_u32 s29, s29, s41
	v_lshl_add_u64 v[28:29], v[2:3], 0, s[4:5]
	v_and_b32_e32 v2, 60, v1
	v_mov_b32_e32 v3, v0
	s_add_u32 s38, s38, s33
	v_lshl_add_u64 v[2:3], s[26:27], 0, v[2:3]
	s_mov_b64 s[4:5], 0x2e300000
	s_addc_u32 s39, s39, 0
	v_lshl_add_u64 v[30:31], v[2:3], 0, s[4:5]
	v_lshlrev_b32_e32 v2, 5, v4
	v_mov_b32_e32 v3, v0
	v_lshlrev_b32_e32 v26, 3, v4
	v_lshl_add_u64 v[4:5], s[38:39], 0, v[2:3]
	s_mov_b64 s[4:5], 0x2000
	v_lshl_add_u64 v[32:33], v[4:5], 0, s[4:5]
	v_lshl_add_u64 v[34:35], s[28:29], 0, v[2:3]
	v_lshl_add_u64 v[36:37], s[24:25], 0, v[2:3]
	global_load_dwordx4 v[80:83], v[32:33], off offset:16
	global_load_dwordx4 v[84:87], v[32:33], off
	global_load_dwordx4 v[88:91], v[34:35], off offset:16
	global_load_dwordx4 v[92:95], v[34:35], off
	global_load_dwordx4 v[96:99], v[36:37], off offset:16
	global_load_dwordx4 v[100:103], v[36:37], off
	s_waitcnt vmcnt(0)
	s_mov_b64 s[38:39], 0
	s_branch .LBB0_808
.LBB0_807:
	s_or_b64 exec, exec, s[40:41]
	s_waitcnt vmcnt(3)
	v_lshlrev_b32_e32 v14, 16, v2
	v_and_b32_e32 v15, 0xffff0000, v2
	v_and_b32_e32 v16, 0xffff0000, v3
	v_lshlrev_b32_e32 v17, 16, v3
	v_mov_b64_e32 v[2:3], s[36:37]
	v_mad_i64_i32 v[2:3], s[4:5], v10, s78, v[2:3]
	v_lshl_add_u64 v[2:3], v[2:3], 0, v[12:13]
	s_mov_b32 s2, 0x26301000
	v_add_co_u32_e32 v2, vcc, s2, v2
	v_and_b32_e32 v18, 0xffff0000, v4
	s_nop 0
	v_addc_co_u32_e32 v3, vcc, 0, v3, vcc
	v_lshlrev_b32_e32 v19, 16, v4
	v_and_b32_e32 v20, 0xffff0000, v5
	v_lshlrev_b32_e32 v21, 16, v5
	v_add_f32_e32 v1, 0, v14
	v_add_f32_e32 v1, v1, v15
	v_add_f32_e32 v1, v1, v17
	v_add_f32_e32 v1, v1, v16
	v_add_f32_e32 v1, v1, v19
	v_add_f32_e32 v1, v1, v18
	v_add_f32_e32 v1, v1, v21
	v_add_f32_e32 v1, v1, v20
	s_waitcnt vmcnt(2)
	v_lshlrev_b32_e32 v54, 16, v6
	v_and_b32_e32 v52, 0xffff0000, v6
	v_add_f32_dpp v1, v1, v1 quad_perm:[1,0,3,2] row_mask:0xf bank_mask:0xf bound_ctrl:1
	v_lshlrev_b32_e32 v50, 16, v7
	v_and_b32_e32 v48, 0xffff0000, v7
	v_add_f32_dpp v1, v1, v1 quad_perm:[2,3,0,1] row_mask:0xf bank_mask:0xf bound_ctrl:1
	v_lshlrev_b32_e32 v46, 16, v8
	v_and_b32_e32 v44, 0xffff0000, v8
	v_add_f32_dpp v1, v1, v1 row_half_mirror row_mask:0xf bank_mask:0xf bound_ctrl:1
	v_lshlrev_b32_e32 v42, 16, v9
	v_and_b32_e32 v40, 0xffff0000, v9
	v_sub_f32_e32 v74, v55, v54
	v_add_u32_e32 v27, s66, v27
	s_mov_b32 s2, 0x1fffff
	s_waitcnt vmcnt(0)
	v_mov_b32_e32 v2, v108
	v_mov_b32_e32 v3, v109
	v_mov_b32_e32 v4, v110
	v_mov_b32_e32 v5, v111
	v_lshlrev_b32_e32 v72, 16, v2
	v_and_b32_e32 v71, 0xffff0000, v2
	v_mul_f32_e32 v2, 0x3c800000, v1
	v_pk_add_f32 v[62:63], v[14:15], v[2:3] op_sel_hi:[1,0] neg_lo:[0,1] neg_hi:[0,1]
	v_lshlrev_b32_e32 v67, 16, v4
	v_and_b32_e32 v66, 0xffff0000, v4
	v_lshlrev_b32_e32 v65, 16, v5
	v_and_b32_e32 v64, 0xffff0000, v5
	v_pk_mul_f32 v[4:5], v[62:63], v[62:63]
	v_pk_add_f32 v[60:61], v[16:17], v[2:3] op_sel_hi:[1,0] neg_lo:[0,1] neg_hi:[0,1]
	v_add_f32_e32 v1, v4, v5
	v_pk_mul_f32 v[6:7], v[60:61], v[60:61]
	v_pk_add_f32 v[58:59], v[18:19], v[2:3] op_sel_hi:[1,0] neg_lo:[0,1] neg_hi:[0,1]
	v_add_f32_e32 v1, v7, v1
	v_pk_mul_f32 v[8:9], v[58:59], v[58:59]
	v_add_f32_e32 v1, v6, v1
	v_pk_add_f32 v[56:57], v[20:21], v[2:3] op_sel_hi:[1,0] neg_lo:[0,1] neg_hi:[0,1]
	v_add_f32_e32 v1, v9, v1
	v_lshlrev_b32_e32 v70, 16, v3
	v_and_b32_e32 v69, 0xffff0000, v3
	v_pk_mul_f32 v[2:3], v[56:57], v[56:57]
	v_add_f32_e32 v1, v8, v1
	v_add_f32_e32 v1, v3, v1
	v_add_f32_e32 v1, v2, v1
	v_mov_b32_e32 v2, 0x3a27c5ac
	s_nop 0
	v_add_f32_dpp v1, v1, v1 quad_perm:[1,0,3,2] row_mask:0xf bank_mask:0xf bound_ctrl:1
	s_nop 1
	v_add_f32_dpp v1, v1, v1 quad_perm:[2,3,0,1] row_mask:0xf bank_mask:0xf bound_ctrl:1
	s_nop 1
	v_add_f32_dpp v1, v1, v1 row_half_mirror row_mask:0xf bank_mask:0xf bound_ctrl:1
	v_fmamk_f32 v1, v1, 0x3c800000, v2
	v_cmp_gt_f32_e32 vcc, s20, v1
	v_mul_f32_e32 v2, 0x4b800000, v1
	s_nop 0
	v_cndmask_b32_e32 v1, v1, v2, vcc
	v_rsq_f32_e32 v1, v1
	s_nop 0
	v_mul_f32_e32 v2, 0x45800000, v1
	v_cndmask_b32_e32 v1, v1, v2, vcc
	v_lshlrev_b64 v[2:3], 6, v[10:11]
	v_lshl_add_u64 v[2:3], v[30:31], 0, v[2:3]
	v_mov_b32_e32 v68, v106
	s_nop 0
	v_mov_b32_e32 v2, v80
	v_mov_b32_e32 v3, v81
	v_mov_b32_e32 v4, v82
	v_mov_b32_e32 v5, v83
	v_mov_b32_e32 v14, v84
	v_mov_b32_e32 v15, v85
	v_mov_b32_e32 v16, v86
	v_mov_b32_e32 v17, v87
	v_mov_b32_e32 v6, v88
	v_mov_b32_e32 v7, v89
	v_mov_b32_e32 v8, v90
	v_mov_b32_e32 v9, v91
	v_mov_b32_e32 v18, v92
	v_mov_b32_e32 v19, v93
	v_mov_b32_e32 v20, v94
	v_mov_b32_e32 v21, v95
	v_mov_b32_e32 v10, v96
	v_mov_b32_e32 v11, v97
	v_mov_b32_e32 v12, v98
	v_mov_b32_e32 v13, v99
	v_mov_b32_e32 v22, v100
	v_mov_b32_e32 v23, v101
	v_mov_b32_e32 v24, v102
	v_mov_b32_e32 v25, v103
	v_pk_mul_f32 v[76:77], v[62:63], v[0:1] op_sel_hi:[0,1]
	v_mov_b32_e32 v75, v77
	v_pk_mul_f32 v[62:63], v[62:63], v[0:1]
	v_cmp_lt_i32_e32 vcc, s2, v27
	s_or_b64 s[38:39], vcc, s[38:39]
	s_waitcnt vmcnt(4)
; __device__ __forceinline__ float sum8(float x) { x += dppf<0xB1>(x); x += dppf<0x4E>(x); x += dppf<0x141>(x); return x; }
; __device__ __forceinline__ void rwkv_post(int l, const bf16_t* PROJ, const bf16_t* LO, bf16_t* YR, const float* BON, int gtid, int nthr) {
;     ...
;     for (int it = gtid; it < TT * 128; it += nthr) {
;         const int T = it >> 7, cgp = it & 127, c0 = 8 * cgp, h = cgp >> 3;
;         float yv[8], zc[8], zp[8], gg[8];
;         unpack8(*(const u32x4*)(YR + (size_t)T * 1024 + c0), yv);
;         const bf16_t* vp = PROJ + (size_t)T * NP + C_RW + 2048 + c0;
;         unpack8(*(const u32x4*)vp, zc);
;         if ((T & (SEQ - 1)) != 0) unpack8(*(const u32x4*)(vp - NP), zp); else {
; #pragma unroll
;             for (int e = 0; e < 8; ++e) zp[e] = 0.f; }
;         unpack8(*(const u32x4*)(LO + (size_t)T * NLORA + 2048 + c0), gg);
;         float sm = 0.f;
; #pragma unroll
;         for (int e = 0; e < 8; ++e) sm += yv[e];
;         const float mean = sum8(sm) * (1.0f / 64.0f);
;         float sq = 0.f;
; #pragma unroll
;         for (int e = 0; e < 8; ++e) { const float d = yv[e] - mean; sq += d * d; }
;         const float rstd = rsqrtf(sum8(sq) * (1.0f / 64.0f) + GN_EPS);
;         const float bon = BON[(size_t)T * 16 + h];
;         const f32x4 m0 = *(const f32x4*)(mu + c0), m1 = *(const f32x4*)(mu + c0 + 4), w0 = *(const f32x4*)(lnw + c0), w1 = *(const f32x4*)(lnw + c0 + 4), b0 = *(const f32x4*)(lnb + c0), b1 = *(const f32x4*)(lnb + c0 + 4);
;         float out[8];
; #pragma unroll
;         for (int e = 0; e < 8; ++e) { const float mm = e < 4 ? m0[e] : m1[e - 4], ww = e < 4 ? w0[e] : w1[e - 4], bb = e < 4 ? b0[e] : b1[e - 4];
;             const float v = zc[e] + (zp[e] - zc[e]) * mm; out[e] = ((yv[e] - mean) * rstd * ww + bb + bon * v) * gg[e]; }
;         *(u32x4*)(YR + (size_t)T * 1024 + c0) = pack8(out);
	v_mov_b32_e32 v76, v14
	s_waitcnt vmcnt(2)
	v_mov_b32_e32 v77, v18
	v_mov_b32_e32 v18, v15
	s_waitcnt vmcnt(0)
	v_mov_b32_e32 v55, v22
	v_pk_fma_f32 v[54:55], v[74:75], v[76:77], v[54:55]
	s_nop 0
	v_fmac_f32_e32 v55, v68, v54
	v_mul_f32_e32 v22, v55, v72
	v_sub_f32_e32 v54, v53, v52
	v_mov_b32_e32 v55, v63
	v_mov_b32_e32 v53, v23
	v_pk_fma_f32 v[14:15], v[54:55], v[18:19], v[52:53]
	v_pk_mul_f32 v[18:19], v[60:61], v[0:1]
	v_fmac_f32_e32 v15, v68, v14
	v_mul_f32_e32 v23, v15, v71
	v_sub_f32_e32 v14, v51, v50
	v_mov_b32_e32 v15, v19
	v_mov_b32_e32 v18, v16
	v_mov_b32_e32 v19, v20
	v_mov_b32_e32 v51, v24
	v_pk_fma_f32 v[14:15], v[14:15], v[18:19], v[50:51]
	v_pk_mul_f32 v[18:19], v[60:61], v[0:1] op_sel_hi:[0,1]
	v_fmac_f32_e32 v15, v68, v14
	v_mul_f32_e32 v24, v15, v70
	v_sub_f32_e32 v14, v49, v48
	v_mov_b32_e32 v15, v19
	v_mov_b32_e32 v20, v17
	v_mov_b32_e32 v49, v25
	v_pk_fma_f32 v[14:15], v[14:15], v[20:21], v[48:49]
	v_pk_mul_f32 v[16:17], v[58:59], v[0:1]
	v_fmac_f32_e32 v15, v68, v14
	v_mul_f32_e32 v18, v15, v69
	v_sub_f32_e32 v14, v47, v46
	v_mov_b32_e32 v15, v17
	v_mov_b32_e32 v16, v2
	v_mov_b32_e32 v17, v6
	v_mov_b32_e32 v47, v10
	v_pk_fma_f32 v[14:15], v[14:15], v[16:17], v[46:47]
	v_pk_mul_f32 v[16:17], v[58:59], v[0:1] op_sel_hi:[0,1]
	v_fmac_f32_e32 v15, v68, v14
	v_mul_f32_e32 v10, v15, v67
	v_sub_f32_e32 v14, v45, v44
	v_mov_b32_e32 v15, v17
	v_mov_b32_e32 v6, v3
	v_mov_b32_e32 v45, v11
	v_pk_fma_f32 v[2:3], v[14:15], v[6:7], v[44:45]
	v_pk_mul_f32 v[6:7], v[56:57], v[0:1]
	v_fmac_f32_e32 v3, v68, v2
	v_mul_f32_e32 v11, v3, v66
	v_sub_f32_e32 v2, v43, v42
	v_mov_b32_e32 v3, v7
	v_mov_b32_e32 v6, v4
	v_mov_b32_e32 v7, v8
	v_mov_b32_e32 v43, v12
	v_pk_fma_f32 v[2:3], v[2:3], v[6:7], v[42:43]
	v_pk_mul_f32 v[6:7], v[56:57], v[0:1] op_sel_hi:[0,1]
	v_fmac_f32_e32 v3, v68, v2
	v_mul_f32_e32 v12, v3, v65
	v_sub_f32_e32 v2, v41, v40
	v_mov_b32_e32 v3, v7
	v_mov_b32_e32 v8, v5
	v_mov_b32_e32 v41, v13
	v_pk_fma_f32 v[2:3], v[2:3], v[8:9], v[40:41]
	s_nop 0
	v_fmac_f32_e32 v3, v68, v2
	v_mul_f32_e32 v1, v3, v64
	v_cvt_pk_bf16_f32 v2, v22, v23
	v_cvt_pk_bf16_f32 v3, v24, v18
	v_cvt_pk_bf16_f32 v4, v10, v11
	v_cvt_pk_bf16_f32 v5, v12, v1
	global_store_dwordx4 v[38:39], v[2:5], off
	s_andn2_b64 exec, exec, s[38:39]
	s_cbranch_execz .LBB0_810
.LBB0_808:
	v_ashrrev_i32_e32 v10, 7, v27
	v_mov_b64_e32 v[6:7], s[34:35]
	v_mad_i64_i32 v[6:7], s[4:5], v10, s88, v[6:7]
	v_lshlrev_b32_e32 v12, 1, v26
	v_mov_b32_e32 v13, v0
	v_ashrrev_i32_e32 v11, 31, v10
	v_lshl_add_u64 v[14:15], v[6:7], 0, v[12:13]
	v_lshlrev_b64 v[2:3], 11, v[10:11]
	v_add_co_u32_e32 v6, vcc, 0xc702000, v14
	v_lshl_add_u64 v[38:39], v[28:29], 0, v[2:3]
	s_nop 0
	v_addc_co_u32_e32 v7, vcc, 0, v15, vcc
	global_load_dwordx4 v[2:5], v[38:39], off
	v_and_b32_e32 v1, 0x7ff80, v27
	global_load_dwordx4 v[6:9], v[6:7], off
	v_mov_b64_e32 v[104:105], s[36:37]
	v_mad_i64_i32 v[104:105], s[4:5], v10, s78, v[104:105]
	v_lshlrev_b64 v[112:113], 6, v[10:11]
	v_lshl_add_u64 v[104:105], v[104:105], 0, v[12:13]
	v_lshl_add_u64 v[112:113], v[30:31], 0, v[112:113]
	v_add_co_u32_e32 v104, vcc, 0x26301000, v104
	s_nop 1
	v_addc_co_u32_e32 v105, vcc, 0, v105, vcc
	global_load_dwordx4 v[108:111], v[104:105], off
	global_load_dword v106, v[112:113], off
	v_cmp_ne_u32_e32 vcc, 0, v1
	v_mov_b32_e32 v55, 0
	v_mov_b32_e32 v53, 0
	v_mov_b32_e32 v51, 0
	v_mov_b32_e32 v49, 0
	v_mov_b32_e32 v47, 0
	v_mov_b32_e32 v45, 0
	v_mov_b32_e32 v43, 0
	v_mov_b32_e32 v41, 0
	s_and_saveexec_b64 s[40:41], vcc
	s_cbranch_execz .LBB0_807
	s_mov_b64 s[4:5], 0xc702000
	v_lshl_add_u64 v[14:15], v[14:15], 0, s[4:5]
	v_add_co_u32_e32 v14, vcc, 0xffffb000, v14
	s_nop 1
	v_addc_co_u32_e32 v15, vcc, -1, v15, vcc
	global_load_dwordx4 v[14:17], v[14:15], off offset:-3072
	s_waitcnt vmcnt(0)
	v_lshlrev_b32_e32 v55, 16, v14
	v_and_b32_e32 v53, 0xffff0000, v14
	v_lshlrev_b32_e32 v51, 16, v15
	v_and_b32_e32 v49, 0xffff0000, v15
	v_lshlrev_b32_e32 v47, 16, v16
	v_and_b32_e32 v45, 0xffff0000, v16
	v_lshlrev_b32_e32 v43, 16, v17
	v_and_b32_e32 v41, 0xffff0000, v17
	s_branch .LBB0_807
